# lever 1: LRU pass-1 item top: artifact lgkmcnt(0) between the first and second LDS row reads removed (all 16 reads pipeline)
# baseline (speedup 1.0000x reference)
; #define LAS __attribute__((address_space(3)))
; #define LDS_WAIT() asm volatile("s_waitcnt lgkmcnt(0)" ::: "memory")
; template <int PASS>
; __device__ __forceinline__ void lru_item(Frame& F, const LAS bf16* lw, const LAS float* prm, const LAS float* cwl, LAS float* xs, LAS unsigned char* pf, int head, int item, int nitem) {
;     ...
;     asm volatile("s_waitcnt vmcnt(0)" ::: "memory");
;     u32x4 vw[4][4];
; #pragma unroll
;     for (int k = 0; k < 4; ++k) {
;         const int rr = r - 1 + k; const bool ok = (rr >= 0) && (rr < 256);
;         const int row = t + k;
; #pragma unroll
;         for (int ks = 0; ks < 4; ++ks) { u32x4 w = *(const LAS u32x4*)(pf + row * 128 + (((2 * ks + hh) ^ ((row >> 1) & 7)) * 16)); if (!ok) w = (u32x4){0u, 0u, 0u, 0u}; vw[k][ks] = w; }
;     }
;     LDS_WAIT(); asm volatile("" ::: "memory");
.LBB0_694:
	v_mov_b32_e32 v111, v108
	s_waitcnt vmcnt(4)
	s_add_i32 s80, s62, s45
	v_and_b32_e32 v110, 31, v111
	v_ashrrev_i32_e32 v112, 5, v111
	v_lshrrev_b32_e32 v1, 1, v111
	v_lshl_add_u32 v0, v110, 7, s46
	v_bitop3_b32 v2, v1, v112, 7 bitop3:0x6c
	v_add_u32_e32 v32, 2, v112
	v_lshl_add_u32 v2, v2, 4, v0
	v_bitop3_b32 v3, v32, v1, 7 bitop3:0x78
	v_add_u32_e32 v33, 4, v112
	v_add_u32_e32 v34, 6, v112
	v_lshl_add_u32 v3, v3, 4, v0
	ds_read_b128 v[20:23], v2
	ds_read_b128 v[8:11], v3
	v_bitop3_b32 v2, v33, v1, 7 bitop3:0x78
	v_bitop3_b32 v1, v34, v1, 7 bitop3:0x78
	v_lshl_add_u32 v2, v2, 4, v0
	v_lshl_add_u32 v0, v1, 4, v0
	ds_read_b128 v[24:27], v2
	ds_read_b128 v[16:19], v0
	v_add_u32_e32 v0, 1, v110
	v_lshl_add_u32 v1, v0, 7, s46
	v_lshrrev_b32_e32 v0, 1, v0
	v_bitop3_b32 v2, v0, v112, 7 bitop3:0x6c
	v_add_u32_e32 v35, 2, v110
	v_lshl_add_u32 v2, v2, 4, v1
	v_bitop3_b32 v3, v0, v32, 7 bitop3:0x6c
	v_lshl_add_u32 v36, v35, 7, s46
	v_lshrrev_b32_e32 v35, 1, v35
	v_lshl_add_u32 v3, v3, 4, v1
	ds_read_b128 v[28:31], v2
	ds_read_b128 v[12:15], v3
	v_bitop3_b32 v2, v0, v33, 7 bitop3:0x6c
	v_bitop3_b32 v0, v0, v34, 7 bitop3:0x6c
	v_bitop3_b32 v37, v35, v112, 7 bitop3:0x6c
	v_lshl_add_u32 v2, v2, 4, v1
	v_lshl_add_u32 v0, v0, 4, v1
	v_lshl_add_u32 v37, v37, 4, v36
	v_bitop3_b32 v38, v35, v32, 7 bitop3:0x6c
	ds_read_b128 v[4:7], v2
	ds_read_b128 v[0:3], v0
	v_lshl_add_u32 v38, v38, 4, v36
	ds_read_b128 v[60:63], v37
	ds_read_b128 v[44:47], v38
	v_bitop3_b32 v37, v35, v33, 7 bitop3:0x6c
	v_bitop3_b32 v35, v35, v34, 7 bitop3:0x6c
	v_lshl_add_u32 v37, v37, 4, v36
	v_lshl_add_u32 v35, v35, 4, v36
	ds_read_b128 v[52:55], v37
	ds_read_b128 v[36:39], v35
	v_add_u32_e32 v35, 3, v110
	v_lshl_add_u32 v48, v35, 7, s46
	v_lshrrev_b32_e32 v35, 1, v35
	v_bitop3_b32 v40, v35, v112, 7 bitop3:0x6c
	v_bitop3_b32 v32, v35, v32, 7 bitop3:0x6c
	v_lshl_add_u32 v40, v40, 4, v48
	v_lshl_add_u32 v32, v32, 4, v48
	ds_read_b128 v[56:59], v40
	ds_read_b128 v[40:43], v32
	v_bitop3_b32 v32, v35, v33, 7 bitop3:0x6c
	v_bitop3_b32 v33, v35, v34, 7 bitop3:0x6c
	v_lshl_add_u32 v32, v32, 4, v48
	v_lshl_add_u32 v33, v33, 4, v48
	ds_read_b128 v[48:51], v32
	ds_read_b128 v[32:35], v33
	s_cmpk_gt_i32 s80, 0x40f
	s_waitcnt lgkmcnt(0)
	s_cselect_b64 s[6:7], -1, 0
	s_cmpk_lt_i32 s80, 0x410
	s_cselect_b32 s12, s80, -1
	s_cmp_lt_i32 s12, 0
	s_cbranch_scc1 .LBB0_702
	s_lshr_b32 s4, s12, 3
	s_mul_hi_u32 s8, s4, 0x3f03f04
	s_mulk_i32 s8, 0x41
	s_sub_i32 s4, s4, s8
	s_mul_hi_u32 s8, s12, 0xfc0fc0fd
	s_lshr_b32 s10, s8, 9
	s_cmp_lt_u32 s4, 64
	s_cselect_b64 s[8:9], -1, 0
	s_lshl_b32 s13, s10, 8
	s_lshl_b32 s10, s10, 14
	s_or_b32 s4, s10, s4
	s_and_b64 s[10:11], s[8:9], exec
	s_cselect_b32 s10, s31, 0x3e300000
	s_cselect_b32 s4, s4, s13
	s_add_u32 s13, s56, s10
	s_addc_u32 s63, s57, 0
	s_lshl_b64 s[10:11], s[4:5], 11
	s_add_u32 s4, s13, s10
	s_addc_u32 s11, s63, s11
	s_add_u32 s10, s4, s34
	s_addc_u32 s11, s11, 0
	s_lshl_b32 s4, s12, 5
	s_and_b32 s4, s4, 0xe0
	v_lshrrev_b32_e32 v64, 4, v111
	s_add_i32 s4, s4, -1
	v_cmp_gt_i32_e32 vcc, s35, v111
	v_xor_b32_e32 v64, v64, v111
	s_and_saveexec_b64 s[12:13], vcc
	s_cbranch_execnz .LBB0_710
	s_or_b64 exec, exec, s[12:13]
	v_cmp_gt_i32_e32 vcc, s36, v111
	s_and_saveexec_b64 s[12:13], vcc
	s_cbranch_execnz .LBB0_711
